# weight-conversion tile loops: prefetch wait moved from right after the loads to the register rotation (first consumer)
# speedup vs baseline: 1.0122x; 1.0122x over previous
.LBB0_13:
	s_and_b64 vcc, exec, s[0:1]
	s_cbranch_vccz .LBB0_504
	v_readlane_b32 s0, v251, 52
	v_readlane_b32 s1, v251, 53
	s_andn2_b64 vcc, exec, s[0:1]
	s_cbranch_vccnz .LBB0_47
	v_ashrrev_i32_e32 v21, 4, v142
	v_readlane_b32 s0, v252, 8
	v_ashrrev_i32_e32 v25, 3, v142
	s_waitcnt vmcnt(0)
	v_lshl_add_u32 v5, v25, 2, 0
	v_add_u32_e32 v0, s0, v21
	v_readlane_b32 s0, v252, 9
	v_readlane_b32 s1, v252, 10
	v_readlane_b32 s33, v250, 0
	v_readlane_b32 s30, v251, 54
	v_mov_b64_e32 v[2:3], s[0:1]
	s_movk_i32 s0, 0x2c00
	v_mad_i64_i32 v[2:3], s[0:1], v0, s0, v[2:3]
	v_lshlrev_b32_e32 v0, 2, v142
	v_and_b32_e32 v4, 60, v0
	v_lshlrev_b32_e32 v0, 2, v4
	v_lshl_add_u64 v[2:3], v[2:3], 0, v[0:1]
	v_add_co_u32_e32 v6, vcc, 0x58000, v2
	s_movk_i32 s0, 0x104
	s_nop 0
	v_addc_co_u32_e32 v7, vcc, 0, v3, vcc
	global_load_dwordx4 v[12:15], v[2:3], off nt
	global_load_dwordx4 v[16:19], v[6:7], off nt
	v_mul_lo_u32 v2, v21, s0
	v_add3_u32 v24, 0, v2, v0
	v_lshlrev_b32_e32 v0, 3, v142
	v_and_b32_e32 v20, 56, v0
	v_mul_u32_u24_e32 v6, 0x104, v20
	v_mov_b32_e32 v2, v1
	v_mov_b32_e32 v3, v1
	v_mov_b32_e32 v0, v1
	v_lshlrev_b32_e32 v22, 2, v4
	v_add_u32_e32 v26, v5, v6
	v_mov_b64_e32 v[6:7], v[2:3]
	v_mov_b64_e32 v[10:11], v[2:3]
	v_mov_b64_e32 v[4:5], v[0:1]
	v_mov_b64_e32 v[8:9], v[0:1]
	v_readlane_b32 s22, v252, 7
	s_waitcnt vmcnt(0)
	s_branch .LBB0_20

.LBB0_19:
	v_ashrrev_i32_e32 v3, 31, v2
	v_readlane_b32 s22, v253, 31
	v_lshlrev_b64 v[2:3], 11, v[2:3]
	v_readlane_b32 s23, v253, 32
	s_ashr_i32 s21, s20, 31
	v_lshlrev_b32_e32 v0, 1, v20
	v_lshl_add_u64 v[2:3], s[22:23], 0, v[2:3]
	v_lshl_add_u64 v[2:3], s[20:21], 1, v[2:3]
	v_lshl_add_u64 v[2:3], v[2:3], 0, v[0:1]
	global_store_dwordx4 v[2:3], v[12:15], off
	s_waitcnt vmcnt(1)
	v_mov_b64_e32 v[18:19], v[10:11]
	s_andn2_b64 vcc, exec, s[2:3]
	v_mov_b64_e32 v[14:15], v[6:7]
	v_mov_b64_e32 v[12:13], v[4:5]
	v_mov_b64_e32 v[16:17], v[8:9]
	s_mov_b32 s30, s35
	s_mov_b32 s22, s36
	s_barrier
	s_cbranch_vccz .LBB0_47

.LBB0_25:
	v_add_u32_e32 v0, 0x2080, v24
	ds_write2_b32 v24, v12, v13 offset1:1
	ds_write2_b32 v24, v14, v15 offset0:2 offset1:3
	ds_write2_b32 v0, v16, v17 offset1:1
	v_add_u32_e32 v0, 0x2088, v24
	ds_write2_b32 v0, v18, v19 offset1:1
	v_add_u32_e32 v0, 0x400, v26
	s_mul_hi_i32 s20, s22, 0x2e8ba2e9
	s_waitcnt lgkmcnt(0)
	s_barrier
	ds_read2_b32 v[12:13], v26 offset1:65
	ds_read2_b32 v[14:15], v26 offset0:130 offset1:195
	ds_read2_b32 v[16:17], v0 offset0:4 offset1:69
	ds_read2_b32 v[2:3], v0 offset0:134 offset1:199
	s_lshr_b32 s21, s20, 31
	s_ashr_i32 s23, s20, 3
	s_add_i32 s23, s23, s21
	s_lshl_b32 s20, s23, 6
	s_cmp_eq_u64 s[92:93], 0
	s_cbranch_scc1 .LBB0_27
	s_ashr_i32 s21, s20, 31
	s_lshl_b64 s[28:29], s[20:21], 2
	s_add_u32 s28, s92, s28
	s_addc_u32 s29, s93, s29
	v_lshlrev_b32_e32 v0, 2, v20
	global_load_dwordx4 v[28:31], v0, s[28:29]
	global_load_dwordx4 v[32:35], v0, s[28:29] offset:16
	s_waitcnt vmcnt(1) lgkmcnt(2)
	v_pk_mul_f32 v[14:15], v[14:15], v[30:31]
	v_pk_mul_f32 v[12:13], v[12:13], v[28:29]
	s_waitcnt vmcnt(0) lgkmcnt(0)
	v_pk_mul_f32 v[2:3], v[2:3], v[34:35]
	v_pk_mul_f32 v[16:17], v[16:17], v[32:33]

.LBB0_333:
	s_lshr_b32 s20, s42, 6
	v_cvt_f32_ubyte0_e32 v0, s20
	v_rcp_iflag_f32_e32 v0, v0
	s_sub_i32 s23, 0, s20
	s_abs_i32 s22, s46
	s_ashr_i32 s21, s46, 31
	v_mul_f32_e32 v0, 0x4f7ffffe, v0
	v_cvt_u32_f32_e32 v0, v0
	v_ashrrev_i32_e32 v21, 4, v142
	v_ashrrev_i32_e32 v25, 3, v142
	v_lshl_add_u32 v5, v25, 2, 0
	v_readfirstlane_b32 s28, v0
	s_mul_i32 s23, s23, s28
	s_mul_hi_u32 s23, s28, s23
	s_add_i32 s28, s28, s23
	s_mul_hi_u32 s23, s22, s28
	s_mul_i32 s28, s23, s20
	s_sub_i32 s22, s22, s28
	s_add_i32 s29, s23, 1
	s_sub_i32 s28, s22, s20
	s_cmp_ge_u32 s22, s20
	s_cselect_b32 s23, s29, s23
	s_cselect_b32 s22, s28, s22
	s_add_i32 s28, s23, 1
	s_cmp_ge_u32 s22, s20
	s_cselect_b32 s22, s28, s23
	s_xor_b32 s22, s22, s21
	s_sub_i32 s21, s22, s21
	s_mul_i32 s20, s21, s20
	v_lshl_add_u32 v0, s21, 6, v21
	s_sub_i32 s22, s46, s20
	v_mad_i64_i32 v[2:3], s[20:21], v0, s42, 0
	v_lshl_add_u64 v[2:3], v[2:3], 2, s[2:3]
	s_lshl_b32 s2, s22, 6
	v_lshlrev_b32_e32 v0, 2, v142
	s_ashr_i32 s3, s2, 31
	v_and_b32_e32 v4, 60, v0
	v_lshl_add_u64 v[2:3], s[2:3], 2, v[2:3]
	v_lshlrev_b32_e32 v0, 2, v4
	v_lshl_add_u64 v[2:3], v[2:3], 0, v[0:1]
	s_lshl_b32 s96, s42, 7
	v_lshl_add_u64 v[6:7], v[2:3], 0, s[96:97]
	global_load_dwordx4 v[16:19], v[2:3], off nt
	global_load_dwordx4 v[12:15], v[6:7], off nt
	s_movk_i32 s2, 0x104
	v_mul_lo_u32 v2, v21, s2
	v_add3_u32 v24, 0, v2, v0
	v_lshlrev_b32_e32 v0, 3, v142
	v_and_b32_e32 v20, 56, v0
	v_mul_u32_u24_e32 v6, 0x104, v20
	v_mov_b32_e32 v2, v1
	v_mov_b32_e32 v3, v1
	v_mov_b32_e32 v0, v1
	v_lshlrev_b32_e32 v22, 2, v4
	v_add_u32_e32 v26, v5, v6
	v_mov_b64_e32 v[6:7], v[2:3]
	v_mov_b64_e32 v[10:11], v[2:3]
	v_readlane_b32 s40, v253, 60
	v_readlane_b32 s41, v250, 37
	v_mov_b64_e32 v[4:5], v[0:1]
	v_mov_b64_e32 v[8:9], v[0:1]
	v_readlane_b32 s68, v250, 42
	s_waitcnt vmcnt(0)
	s_branch .LBB0_338

.LBB0_337:
	v_mad_i64_i32 v[2:3], s[22:23], v2, s33, 0
	v_lshl_add_u64 v[2:3], v[2:3], 1, s[0:1]
	s_ashr_i32 s43, s42, 31
	v_lshl_add_u64 v[2:3], s[42:43], 1, v[2:3]
	v_lshlrev_b32_e32 v0, 1, v20
	v_lshl_add_u64 v[2:3], v[2:3], 0, v[0:1]
	global_store_dwordx4 v[2:3], v[12:15], off sc1
	s_waitcnt vmcnt(1)
	v_mov_b64_e32 v[18:19], v[6:7]
	s_add_i32 s40, s40, s68
	v_mov_b64_e32 v[14:15], v[10:11]
	s_and_b64 vcc, exec, s[38:39]
	v_mov_b64_e32 v[16:17], v[4:5]
	v_mov_b64_e32 v[12:13], v[8:9]
	s_mov_b64 s[0:1], s[30:31]
	s_mov_b64 s[36:37], s[28:29]
	s_mov_b32 s33, s45
	s_mov_b32 s42, s20
	s_mov_b32 s35, s44
	s_mov_b32 s46, s64
	s_barrier
	s_cbranch_vccnz .LBB0_370

.LBB0_349:
	s_ashr_i32 s21, s42, 6
	s_abs_i32 s22, s21
	v_cvt_f32_u32_e32 v0, s22
	s_sub_i32 s43, 0, s22
	s_abs_i32 s23, s46
	s_xor_b32 s42, s46, s21
	v_rcp_iflag_f32_e32 v0, v0
	s_ashr_i32 s42, s42, 31
	ds_write2_b32 v24, v16, v17 offset1:1
	ds_write2_b32 v24, v18, v19 offset0:2 offset1:3
	v_add_u32_e32 v2, 0x2080, v24
	v_mul_f32_e32 v0, 0x4f7ffffe, v0
	v_cvt_u32_f32_e32 v0, v0
	ds_write2_b32 v2, v12, v13 offset1:1
	v_readfirstlane_b32 s47, v0
	s_mul_i32 s43, s43, s47
	s_mul_hi_u32 s43, s47, s43
	s_add_i32 s47, s47, s43
	s_mul_hi_u32 s43, s23, s47
	s_mul_i32 s47, s43, s22
	s_sub_i32 s23, s23, s47
	s_add_i32 s65, s43, 1
	s_sub_i32 s47, s23, s22
	s_cmp_ge_u32 s23, s22
	s_cselect_b32 s43, s65, s43
	s_cselect_b32 s23, s47, s23
	s_add_i32 s47, s43, 1
	v_add_u32_e32 v0, 0x2088, v24
	s_cmp_ge_u32 s23, s22
	ds_write2_b32 v0, v14, v15 offset1:1
	v_add_u32_e32 v0, 0x400, v26
	s_cselect_b32 s22, s47, s43
	s_waitcnt lgkmcnt(0)
	s_barrier
	ds_read2_b32 v[12:13], v26 offset1:65
	ds_read2_b32 v[14:15], v26 offset0:130 offset1:195
	ds_read2_b32 v[16:17], v0 offset0:4 offset1:69
	ds_read2_b32 v[2:3], v0 offset0:134 offset1:199
	s_xor_b32 s22, s22, s42
	s_sub_i32 s22, s22, s42
	s_lshl_b32 s42, s22, 6
	s_cmp_eq_u64 s[36:37], 0
	s_cbranch_scc1 .LBB0_351
	s_ashr_i32 s43, s42, 31
	s_lshl_b64 s[66:67], s[42:43], 2
	s_add_u32 s36, s36, s66
	s_addc_u32 s37, s37, s67
	v_lshlrev_b32_e32 v0, 2, v20
	global_load_dwordx4 v[28:31], v0, s[36:37]
	global_load_dwordx4 v[32:35], v0, s[36:37] offset:16
	s_waitcnt vmcnt(1) lgkmcnt(2)
	v_pk_mul_f32 v[14:15], v[14:15], v[30:31]
	v_pk_mul_f32 v[12:13], v[12:13], v[28:29]
	s_waitcnt vmcnt(0) lgkmcnt(0)
	v_pk_mul_f32 v[2:3], v[2:3], v[34:35]
	v_pk_mul_f32 v[16:17], v[16:17], v[32:33]

.LBB0_382:
	s_lshr_b32 s22, s42, 6
	v_cvt_f32_ubyte0_e32 v0, s22
	v_rcp_iflag_f32_e32 v0, v0
	s_sub_i32 s29, 0, s22
	s_abs_i32 s28, s45
	s_ashr_i32 s23, s45, 31
	v_mul_f32_e32 v0, 0x4f7ffffe, v0
	v_cvt_u32_f32_e32 v0, v0
	v_ashrrev_i32_e32 v21, 4, v142
	v_ashrrev_i32_e32 v25, 3, v142
	v_lshl_add_u32 v5, v25, 2, 0
	v_readfirstlane_b32 s30, v0
	s_mul_i32 s29, s29, s30
	s_mul_hi_u32 s29, s30, s29
	s_add_i32 s30, s30, s29
	s_mul_hi_u32 s29, s28, s30
	s_mul_i32 s30, s29, s22
	s_sub_i32 s28, s28, s30
	s_add_i32 s31, s29, 1
	s_sub_i32 s30, s28, s22
	s_cmp_ge_u32 s28, s22
	s_cselect_b32 s29, s31, s29
	s_cselect_b32 s28, s30, s28
	s_add_i32 s30, s29, 1
	s_cmp_ge_u32 s28, s22
	s_cselect_b32 s28, s30, s29
	s_xor_b32 s28, s28, s23
	s_sub_i32 s23, s28, s23
	s_mul_i32 s22, s23, s22
	v_lshl_add_u32 v0, s23, 6, v21
	s_sub_i32 s28, s45, s22
	v_mad_i64_i32 v[2:3], s[22:23], v0, s42, 0
	v_lshl_add_u64 v[2:3], v[2:3], 2, s[20:21]
	s_lshl_b32 s20, s28, 6
	v_lshlrev_b32_e32 v0, 2, v142
	s_ashr_i32 s21, s20, 31
	v_and_b32_e32 v4, 60, v0
	v_lshl_add_u64 v[2:3], s[20:21], 2, v[2:3]
	v_lshlrev_b32_e32 v0, 2, v4
	v_lshl_add_u64 v[2:3], v[2:3], 0, v[0:1]
	s_lshl_b32 s96, s42, 7
	v_lshl_add_u64 v[6:7], v[2:3], 0, s[96:97]
	global_load_dwordx4 v[16:19], v[2:3], off nt
	global_load_dwordx4 v[12:15], v[6:7], off nt
	s_movk_i32 s20, 0x104
	v_mul_lo_u32 v2, v21, s20
	v_add3_u32 v24, 0, v2, v0
	v_lshlrev_b32_e32 v0, 3, v142
	v_and_b32_e32 v20, 56, v0
	v_mul_u32_u24_e32 v6, 0x104, v20
	v_mov_b32_e32 v2, v1
	v_mov_b32_e32 v3, v1
	v_mov_b32_e32 v0, v1
	v_lshlrev_b32_e32 v22, 2, v4
	v_add_u32_e32 v26, v5, v6
	v_mov_b64_e32 v[6:7], v[2:3]
	v_mov_b64_e32 v[10:11], v[2:3]
	v_readlane_b32 s33, v253, 61
	v_readlane_b32 s35, v250, 45
	v_mov_b64_e32 v[4:5], v[0:1]
	v_mov_b64_e32 v[8:9], v[0:1]
	s_waitcnt vmcnt(0)
	s_branch .LBB0_387

.LBB0_386:
	v_ashrrev_i32_e32 v3, 31, v2
	v_lshlrev_b64 v[2:3], 11, v[2:3]
	v_lshl_add_u64 v[2:3], s[0:1], 0, v[2:3]
	s_ashr_i32 s43, s42, 31
	v_lshl_add_u64 v[2:3], s[42:43], 1, v[2:3]
	v_lshlrev_b32_e32 v0, 1, v20
	v_lshl_add_u64 v[2:3], v[2:3], 0, v[0:1]
	global_store_dwordx4 v[2:3], v[12:15], off sc1
	s_waitcnt vmcnt(1)
	v_readlane_b32 s0, v250, 63
	v_mov_b64_e32 v[18:19], v[6:7]
	v_mov_b64_e32 v[14:15], v[10:11]
	s_add_i32 s33, s33, s0
	s_and_b64 vcc, exec, s[38:39]
	v_mov_b64_e32 v[16:17], v[4:5]
	v_mov_b64_e32 v[12:13], v[8:9]
	s_mov_b64 s[0:1], s[36:37]
	s_mov_b64 s[2:3], s[30:31]
	s_mov_b32 s42, s28
	s_mov_b32 s40, s41
	s_mov_b32 s45, s44
	s_barrier
	s_cbranch_vccnz .LBB0_423

.LBB0_402:
	s_ashr_i32 s22, s42, 6
	s_abs_i32 s23, s22
	v_cvt_f32_u32_e32 v0, s23
	s_sub_i32 s43, 0, s23
	s_abs_i32 s29, s45
	s_xor_b32 s42, s45, s22
	v_rcp_iflag_f32_e32 v0, v0
	s_ashr_i32 s42, s42, 31
	ds_write2_b32 v24, v16, v17 offset1:1
	ds_write2_b32 v24, v18, v19 offset0:2 offset1:3
	v_add_u32_e32 v2, 0x2080, v24
	v_mul_f32_e32 v0, 0x4f7ffffe, v0
	v_cvt_u32_f32_e32 v0, v0
	ds_write2_b32 v2, v12, v13 offset1:1
	v_readfirstlane_b32 s46, v0
	s_mul_i32 s43, s43, s46
	s_mul_hi_u32 s43, s46, s43
	s_add_i32 s46, s46, s43
	s_mul_hi_u32 s43, s29, s46
	s_mul_i32 s46, s43, s23
	s_sub_i32 s29, s29, s46
	s_add_i32 s47, s43, 1
	s_sub_i32 s46, s29, s23
	s_cmp_ge_u32 s29, s23
	s_cselect_b32 s43, s47, s43
	s_cselect_b32 s29, s46, s29
	s_add_i32 s46, s43, 1
	v_add_u32_e32 v0, 0x2088, v24
	s_cmp_ge_u32 s29, s23
	ds_write2_b32 v0, v14, v15 offset1:1
	v_add_u32_e32 v0, 0x400, v26
	s_cselect_b32 s23, s46, s43
	s_waitcnt lgkmcnt(0)
	s_barrier
	ds_read2_b32 v[12:13], v26 offset1:65
	ds_read2_b32 v[14:15], v26 offset0:130 offset1:195
	ds_read2_b32 v[16:17], v0 offset0:4 offset1:69
	ds_read2_b32 v[2:3], v0 offset0:134 offset1:199
	s_xor_b32 s23, s23, s42
	s_sub_i32 s23, s23, s42
	s_lshl_b32 s42, s23, 6
	s_cmp_eq_u64 s[2:3], 0
	s_cbranch_scc1 .LBB0_404
	s_ashr_i32 s43, s42, 31
	s_lshl_b64 s[46:47], s[42:43], 2
	s_add_u32 s2, s2, s46
	s_addc_u32 s3, s3, s47
	v_lshlrev_b32_e32 v0, 2, v20
	global_load_dwordx4 v[28:31], v0, s[2:3]
	global_load_dwordx4 v[32:35], v0, s[2:3] offset:16
	s_waitcnt vmcnt(1) lgkmcnt(2)
	v_pk_mul_f32 v[14:15], v[14:15], v[30:31]
	v_pk_mul_f32 v[12:13], v[12:13], v[28:29]
	s_waitcnt vmcnt(0) lgkmcnt(0)
	v_pk_mul_f32 v[2:3], v[2:3], v[34:35]
	v_pk_mul_f32 v[16:17], v[16:17], v[32:33]

.LBB0_448:
	s_lshr_b32 s20, s43, 6
	v_cvt_f32_ubyte0_e32 v0, s20
	v_rcp_iflag_f32_e32 v0, v0
	s_sub_i32 s23, 0, s20
	s_abs_i32 s22, s42
	s_ashr_i32 s21, s42, 31
	v_mul_f32_e32 v0, 0x4f7ffffe, v0
	v_cvt_u32_f32_e32 v0, v0
	v_ashrrev_i32_e32 v21, 4, v142
	v_ashrrev_i32_e32 v25, 3, v142
	v_lshl_add_u32 v5, v25, 2, 0
	v_readfirstlane_b32 s28, v0
	s_mul_i32 s23, s23, s28
	s_mul_hi_u32 s23, s28, s23
	s_add_i32 s28, s28, s23
	s_mul_hi_u32 s23, s22, s28
	s_mul_i32 s28, s23, s20
	s_sub_i32 s22, s22, s28
	s_add_i32 s29, s23, 1
	s_sub_i32 s28, s22, s20
	s_cmp_ge_u32 s22, s20
	s_cselect_b32 s23, s29, s23
	s_cselect_b32 s22, s28, s22
	s_add_i32 s28, s23, 1
	s_cmp_ge_u32 s22, s20
	s_cselect_b32 s22, s28, s23
	s_xor_b32 s22, s22, s21
	s_sub_i32 s21, s22, s21
	s_mul_i32 s20, s21, s20
	v_lshl_add_u32 v0, s21, 6, v21
	s_sub_i32 s22, s42, s20
	v_mad_i64_i32 v[2:3], s[20:21], v0, s43, 0
	v_lshl_add_u64 v[2:3], v[2:3], 2, s[2:3]
	s_lshl_b32 s2, s22, 6
	v_lshlrev_b32_e32 v0, 2, v142
	s_ashr_i32 s3, s2, 31
	v_and_b32_e32 v4, 60, v0
	v_lshl_add_u64 v[2:3], s[2:3], 2, v[2:3]
	v_lshlrev_b32_e32 v0, 2, v4
	v_lshl_add_u64 v[2:3], v[2:3], 0, v[0:1]
	s_lshl_b32 s96, s43, 7
	v_lshl_add_u64 v[6:7], v[2:3], 0, s[96:97]
	global_load_dwordx4 v[16:19], v[2:3], off nt
	global_load_dwordx4 v[12:15], v[6:7], off nt
	s_movk_i32 s2, 0x104
	v_mul_lo_u32 v2, v21, s2
	v_add3_u32 v24, 0, v2, v0
	v_lshlrev_b32_e32 v0, 3, v142
	v_and_b32_e32 v20, 56, v0
	v_mul_u32_u24_e32 v6, 0x104, v20
	v_mov_b32_e32 v2, v1
	v_mov_b32_e32 v3, v1
	v_mov_b32_e32 v0, v1
	v_lshlrev_b32_e32 v22, 2, v4
	v_add_u32_e32 v26, v5, v6
	v_mov_b64_e32 v[6:7], v[2:3]
	v_mov_b64_e32 v[10:11], v[2:3]
	v_readlane_b32 s35, v250, 15
	v_mov_b64_e32 v[4:5], v[0:1]
	v_mov_b64_e32 v[8:9], v[0:1]
	s_waitcnt vmcnt(0)
	s_branch .LBB0_453

.LBB0_452:
	v_mad_i64_i32 v[2:3], s[22:23], v2, s33, 0
	v_lshl_add_u64 v[2:3], v[2:3], 1, s[0:1]
	s_ashr_i32 s39, s38, 31
	v_lshl_add_u64 v[2:3], s[38:39], 1, v[2:3]
	v_lshlrev_b32_e32 v0, 1, v20
	v_lshl_add_u64 v[2:3], v[2:3], 0, v[0:1]
	global_store_dwordx4 v[2:3], v[12:15], off sc1
	s_waitcnt vmcnt(1)
	v_mov_b64_e32 v[18:19], v[6:7]
	s_cmpk_lt_i32 s35, 0x840
	v_mov_b64_e32 v[14:15], v[10:11]
	v_mov_b64_e32 v[16:17], v[4:5]
	v_mov_b64_e32 v[12:13], v[8:9]
	s_mov_b64 s[0:1], s[30:31]
	s_mov_b64 s[36:37], s[20:21]
	s_mov_b32 s33, s45
	s_mov_b32 s43, s28
	s_mov_b32 s40, s44
	s_mov_b32 s42, s41
	s_barrier
	s_cbranch_scc0 .LBB0_484

.LBB0_461:
	s_ashr_i32 s22, s43, 6
	s_abs_i32 s23, s22
	v_cvt_f32_u32_e32 v0, s23
	s_sub_i32 s39, 0, s23
	s_abs_i32 s29, s42
	s_xor_b32 s38, s42, s22
	v_rcp_iflag_f32_e32 v0, v0
	s_ashr_i32 s38, s38, 31
	ds_write2_b32 v24, v16, v17 offset1:1
	ds_write2_b32 v24, v18, v19 offset0:2 offset1:3
	v_add_u32_e32 v2, 0x2080, v24
	v_mul_f32_e32 v0, 0x4f7ffffe, v0
	v_cvt_u32_f32_e32 v0, v0
	ds_write2_b32 v2, v12, v13 offset1:1
	v_readfirstlane_b32 s43, v0
	s_mul_i32 s39, s39, s43
	s_mul_hi_u32 s39, s43, s39
	s_add_i32 s43, s43, s39
	s_mul_hi_u32 s39, s29, s43
	s_mul_i32 s43, s39, s23
	s_sub_i32 s29, s29, s43
	s_add_i32 s46, s39, 1
	s_sub_i32 s43, s29, s23
	s_cmp_ge_u32 s29, s23
	s_cselect_b32 s39, s46, s39
	s_cselect_b32 s29, s43, s29
	s_add_i32 s43, s39, 1
	v_add_u32_e32 v0, 0x2088, v24
	s_cmp_ge_u32 s29, s23
	ds_write2_b32 v0, v14, v15 offset1:1
	v_add_u32_e32 v0, 0x400, v26
	s_cselect_b32 s23, s43, s39
	s_waitcnt lgkmcnt(0)
	s_barrier
	ds_read2_b32 v[12:13], v26 offset1:65
	ds_read2_b32 v[14:15], v26 offset0:130 offset1:195
	ds_read2_b32 v[16:17], v0 offset0:4 offset1:69
	ds_read2_b32 v[2:3], v0 offset0:134 offset1:199
	s_xor_b32 s23, s23, s38
	s_sub_i32 s23, s23, s38
	s_lshl_b32 s38, s23, 6
	s_cmp_eq_u64 s[36:37], 0
	s_cbranch_scc1 .LBB0_463
	s_ashr_i32 s39, s38, 31
	s_lshl_b64 s[46:47], s[38:39], 2
	s_add_u32 s36, s36, s46
	s_addc_u32 s37, s37, s47
	v_lshlrev_b32_e32 v0, 2, v20
	global_load_dwordx4 v[28:31], v0, s[36:37]
	global_load_dwordx4 v[32:35], v0, s[36:37] offset:16
	s_waitcnt vmcnt(1) lgkmcnt(2)
	v_pk_mul_f32 v[14:15], v[14:15], v[30:31]
	v_pk_mul_f32 v[12:13], v[12:13], v[28:29]
	s_waitcnt vmcnt(0) lgkmcnt(0)
	v_pk_mul_f32 v[2:3], v[2:3], v[34:35]
	v_pk_mul_f32 v[16:17], v[16:17], v[32:33]

.LBB0_484:
	v_readlane_b32 s0, v250, 23
	v_readlane_b32 s1, v250, 24
	v_readlane_b32 s44, v255, 0
	s_andn2_b64 vcc, exec, s[0:1]
	v_readlane_b32 s40, v254, 63
	s_mov_b32 s41, s25
	v_readlane_b32 s25, v250, 22
	v_readlane_b32 s45, v255, 1
	s_cbranch_vccnz .LBB0_503
	v_ashrrev_i32_e32 v21, 4, v142
	v_readlane_b32 s0, v250, 26
	v_ashrrev_i32_e32 v25, 3, v142
	v_lshl_add_u32 v5, v25, 2, 0
	v_add_u32_e32 v0, s0, v21
	v_readlane_b32 s0, v250, 27
	v_readlane_b32 s1, v250, 28
	v_readlane_b32 s2, v250, 25
	s_mov_b32 s28, s2
	v_mov_b64_e32 v[2:3], s[0:1]
	s_movk_i32 s0, 0x7000
	v_mad_i64_i32 v[2:3], s[0:1], v0, s0, v[2:3]
	v_lshlrev_b32_e32 v0, 2, v142
	v_and_b32_e32 v4, 60, v0
	v_lshlrev_b32_e32 v0, 2, v4
	v_lshl_add_u64 v[2:3], v[2:3], 0, v[0:1]
	v_add_co_u32_e32 v6, vcc, 0xe0000, v2
	s_movk_i32 s0, 0x104
	s_nop 0
	v_addc_co_u32_e32 v7, vcc, 0, v3, vcc
	global_load_dwordx4 v[12:15], v[2:3], off nt
	global_load_dwordx4 v[16:19], v[6:7], off nt
	v_mul_lo_u32 v2, v21, s0
	v_add3_u32 v24, 0, v2, v0
	v_lshlrev_b32_e32 v0, 3, v142
	v_and_b32_e32 v20, 56, v0
	v_mul_u32_u24_e32 v6, 0x104, v20
	v_mov_b32_e32 v2, v1
	v_mov_b32_e32 v3, v1
	v_mov_b32_e32 v0, v1
	v_lshlrev_b32_e32 v22, 2, v4
	v_add_u32_e32 v26, v5, v6
	v_mov_b64_e32 v[6:7], v[2:3]
	v_mov_b64_e32 v[10:11], v[2:3]
	v_mov_b64_e32 v[4:5], v[0:1]
	v_mov_b64_e32 v[8:9], v[0:1]
	s_waitcnt vmcnt(0)
	s_branch .LBB0_489

.LBB0_488:
	s_or_b64 exec, exec, s[2:3]
	v_ashrrev_i32_e32 v3, 31, v2
	v_lshlrev_b64 v[2:3], 11, v[2:3]
	v_lshl_add_u64 v[2:3], s[44:45], 0, v[2:3]
	s_ashr_i32 s1, s0, 31
	v_lshl_add_u64 v[2:3], s[0:1], 1, v[2:3]
	v_lshlrev_b32_e32 v0, 1, v20
	v_lshl_add_u64 v[2:3], v[2:3], 0, v[0:1]
	global_store_dwordx4 v[2:3], v[12:15], off sc1
	s_waitcnt vmcnt(1)
	s_add_i32 s28, s28, s25
	v_mov_b64_e32 v[18:19], v[10:11]
	v_mov_b64_e32 v[14:15], v[6:7]
	s_cmpk_gt_i32 s28, 0x43f
	v_mov_b64_e32 v[12:13], v[4:5]
	v_mov_b64_e32 v[16:17], v[8:9]
	s_mov_b32 s2, s29
	s_barrier
	s_cbranch_scc1 .LBB0_503

.LBB0_493:
	v_add_u32_e32 v0, 0x2080, v24
	ds_write2_b32 v24, v12, v13 offset1:1
	ds_write2_b32 v24, v14, v15 offset0:2 offset1:3
	ds_write2_b32 v0, v16, v17 offset1:1
	v_add_u32_e32 v0, 0x2088, v24
	s_mul_hi_i32 s0, s2, 0x92492493
	ds_write2_b32 v0, v18, v19 offset1:1
	v_add_u32_e32 v0, 0x400, v26
	s_add_i32 s0, s0, s2
	s_waitcnt lgkmcnt(0)
	s_barrier
	ds_read2_b32 v[2:3], v26 offset1:65
	ds_read2_b32 v[14:15], v26 offset0:130 offset1:195
	ds_read2_b32 v[16:17], v0 offset0:4 offset1:69
	ds_read2_b32 v[18:19], v0 offset0:134 offset1:199
	s_lshr_b32 s1, s0, 31
	s_ashr_i32 s3, s0, 6
	s_add_i32 s3, s3, s1
	v_readlane_b32 s64, v251, 55
	s_lshl_b32 s0, s3, 6
	v_readlane_b32 s70, v251, 61
	v_readlane_b32 s71, v251, 62
	s_cmp_eq_u64 s[70:71], 0
	v_readlane_b32 s65, v251, 56
	v_readlane_b32 s66, v251, 57
	v_readlane_b32 s67, v251, 58
	v_readlane_b32 s68, v251, 59
	v_readlane_b32 s69, v251, 60
	v_readlane_b32 s72, v251, 63
	v_readlane_b32 s73, v252, 0
	v_readlane_b32 s74, v252, 1
	v_readlane_b32 s75, v252, 2
	v_readlane_b32 s76, v252, 3
	v_readlane_b32 s77, v252, 4
	v_readlane_b32 s78, v252, 5
	v_readlane_b32 s79, v252, 6
	s_cbranch_scc1 .LBB0_495
	s_ashr_i32 s1, s0, 31
	s_lshl_b64 s[20:21], s[0:1], 2
	s_add_u32 s20, s70, s20
	s_addc_u32 s21, s71, s21
	v_lshlrev_b32_e32 v0, 2, v20
	global_load_dwordx4 v[28:31], v0, s[20:21]
	global_load_dwordx4 v[32:35], v0, s[20:21] offset:16
	s_waitcnt vmcnt(1) lgkmcnt(2)
	v_pk_mul_f32 v[14:15], v[14:15], v[30:31]
	v_pk_mul_f32 v[2:3], v[2:3], v[28:29]
	s_waitcnt vmcnt(0) lgkmcnt(0)
	v_pk_mul_f32 v[18:19], v[18:19], v[34:35]
	v_pk_mul_f32 v[16:17], v[16:17], v[32:33]
